# v67 + code placement: WIN shifted by 4 bytes
# baseline (speedup 1.0000x reference)
.LBB0_1003:
	s_nop 0
	s_cmp_lt_i32 s58, 11
	s_cselect_b64 s[0:1], -1, 0
	s_and_b64 s[2:3], s[0:1], s[4:5]
	s_andn2_b64 vcc, exec, s[2:3]
	s_cbranch_vccnz .LBB0_1041
	s_cmpk_gt_i32 s94, 0x63f
	v_readfirstlane_b32 s5, v0
	s_cbranch_scc1 .LBB0_1041
	v_lshrrev_b32_e32 v1, 5, v0
	v_lshrrev_b32_e32 v3, 1, v0
	v_and_b32_e32 v1, 4, v1
	v_bfe_u32 v2, v0, 2, 2
	v_and_b32_e32 v3, 24, v3
	s_add_u32 s3, s56, 0x300000
	s_movk_i32 s2, 0x200
	v_or3_b32 v1, v1, v2, v3
	v_bfe_u32 v3, v0, 3, 25
	s_addc_u32 s35, s57, 0
	v_or_b32_e32 v3, 64, v3
	s_movk_i32 s4, 0x60
	v_cmp_gt_u32_e32 vcc, s2, v0
	v_bfe_u32 v12, v0, 2, 4
	s_movk_i32 s2, 0x70
	s_ashr_i32 s71, s94, 31
	v_and_or_b32 v4, v3, s4, v1
	v_and_or_b32 v3, v3, s2, v12
	s_lshr_b32 s2, s71, 29
	s_add_i32 s2, s94, s2
	s_lshr_b32 s6, s5, 6
	s_and_b32 s4, s2, -8
	s_lshr_b32 s14, s5, 8
	s_lshl_b32 s70, s6, 10
	s_sub_i32 s4, s94, s4
	s_cmp_lt_i32 s4, 0
	s_movk_i32 s72, 0xc9
	s_cselect_b32 s7, s72, 0xc8
	s_mul_i32 s4, s4, s7
	s_ashr_i32 s2, s2, 3
	s_add_i32 s4, s4, s2
	s_mul_hi_i32 s2, s4, 0x66666667
	s_lshr_b32 s7, s2, 31
	s_ashr_i32 s2, s2, 6
	s_add_i32 s2, s2, s7
	s_mul_i32 s7, s2, 0xa0
	s_sub_i32 s7, s4, s7
	s_sext_i32_i16 s4, s7
	s_bfe_u32 s4, s4, 0x3001c
	s_add_i32 s8, s7, s4
	s_sext_i32_i16 s4, s8
	s_and_b32 s8, s8, 0xfff8
	v_lshlrev_b32_e32 v4, 11, v4
	s_sub_i32 s7, s7, s8
	v_or_b32_e32 v5, 0xfffc0000, v4
	s_lshl_b32 s2, s2, 3
	s_sext_i32_i16 s7, s7
	v_lshlrev_b32_e32 v2, 4, v0
	v_cndmask_b32_e32 v4, v5, v4, vcc
	v_and_b32_e32 v5, 32, v0
	s_add_i32 s2, s2, s7
	v_bitop3_b32 v10, v2, v5, 48 bitop3:0x6c
	v_and_b32_e32 v11, 64, v0
	s_lshr_b32 s4, s4, 3
	s_lshl_b32 s8, s2, 8
	v_or_b32_e32 v2, v10, v11
	v_lshlrev_b32_e32 v3, 11, v3
	s_ashr_i32 s9, s8, 31
	s_bfe_i64 s[10:11], s[4:5], 0x100000
	v_or_b32_e32 v146, v4, v2
	v_or_b32_e32 v4, 0xfffc0000, v3
	s_lshl_b64 s[8:9], s[8:9], 11
	s_lshl_b64 s[10:11], s[10:11], 19
	v_cndmask_b32_e32 v13, v4, v3, vcc
	v_lshrrev_b32_e32 v3, 3, v0
	s_add_u32 s66, s3, s10
	v_and_or_b32 v1, v3, 32, v1
	s_addc_u32 s67, s35, s11
	s_add_i32 s73, s70, 0
	v_lshl_or_b32 v150, v1, 11, v2
	s_add_i32 m0, s73, 0x10000
	v_and_or_b32 v1, v3, 48, v12
	global_load_lds_dwordx4 v150, s[66:67]
	s_add_i32 m0, s73, 0x12000
	s_add_u32 s10, s66, 0x40000
	global_load_lds_dwordx4 v146, s[66:67]
	s_addc_u32 s11, s67, 0
	s_add_i32 m0, s73, 0x14000
	v_lshl_or_b32 v152, v1, 11, v2
	global_load_lds_dwordx4 v150, s[10:11]
	s_add_i32 m0, s73, 0x16000
	s_add_u32 s64, s96, s8
	s_addc_u32 s65, s97, s9
	s_add_i32 s74, s73, 0x2000
	global_load_lds_dwordx4 v146, s[10:11]
	s_mov_b32 m0, s73
	s_add_u32 s8, s64, 0x40000
	v_or_b32_e32 v148, v13, v2
	global_load_lds_dwordx4 v152, s[64:65]
	s_mov_b32 m0, s74
	s_addc_u32 s9, s65, 0
	s_add_i32 s75, s73, 0x4000
	global_load_lds_dwordx4 v148, s[64:65]
	s_mov_b32 m0, s75
	s_add_i32 s76, s73, 0x6000
	global_load_lds_dwordx4 v152, s[8:9]
	s_mov_b32 m0, s76
	v_mov_b32_e32 v155, 0
	global_load_lds_dwordx4 v148, s[8:9]
	v_mov_b32_e32 v151, v155
	v_mov_b32_e32 v147, v155
	v_mov_b32_e32 v153, v155
	v_mov_b32_e32 v149, v155
	s_cmp_eq_u32 s14, 1
	s_mov_b32 s7, 0
	v_lshl_add_u64 v[8:9], s[66:67], 0, v[150:151]
	v_lshl_add_u64 v[6:7], s[66:67], 0, v[146:147]
	v_lshl_add_u64 v[2:3], s[64:65], 0, v[152:153]
	s_cselect_b64 s[8:9], -1, 0
	s_cmp_lg_u32 s14, 1
	v_lshl_add_u64 v[4:5], s[64:65], 0, v[148:149]
	s_cbranch_scc1 .LBB0_1007
	s_barrier
